# weight conversion tiles: both 32-row loads of a tile issued together (previous label was attached to a timing probe by mistake)
# speedup vs baseline: 1.0369x; 1.0025x over previous
; #define OPAQUE(x) asm volatile("" : "+v"(x))
; #define TIDX(p) ((p).wv * 64 + (int)__builtin_amdgcn_mbcnt_hi(~0u, __builtin_amdgcn_mbcnt_lo(~0u, 0u)))
; DI unsigned pack2(float a, float b) { f32x2_t v = {a, b}; bf16x2_t r = __builtin_convertvector(v, bf16x2_t); return __builtin_bit_cast(unsigned, r); }
; DI void cvt_tile(const PX& p, const float* __restrict__ src, bfu* __restrict__ dst, int K, int N, int tile, float* t, bool perm_in = false) {
;   const int ntn = (N + 63) >> 6;
;   const int kt = tile / ntn, nt = tile - kt * ntn;
;   const int k0 = kt * 64, n0 = nt * 64;
;   int tidc = TIDX(p); OPAQUE(tidc);
;   __syncthreads();
; #pragma unroll
;   for (int i = 0; i < 2; i++) {
;     const int idx = tidc + i * NTHR;
;     const int kk = idx >> 4, n4 = (idx & 15) * 4, n = n0 + n4;
;     float4 v = make_float4(0.f, 0.f, 0.f, 0.f);
;     if (n < N) v = *(const float4*)(src + (size_t)(k0 + kk) * N + n);
;     t[kk * 65 + n4] = v.x; t[kk * 65 + n4 + 1] = v.y; t[kk * 65 + n4 + 2] = v.z; t[kk * 65 + n4 + 3] = v.w;
;   }
;   __syncthreads();
;   {
;     const int nn = tidc >> 3, k8 = (tidc & 7) * 8, n = n0 + nn;
;     if (n < N) {
;       uint4 o;
;       o.x = pack2(t[(k8 + 0) * 65 + nn], t[(k8 + 1) * 65 + nn]);
;       o.y = pack2(t[(k8 + 2) * 65 + nn], t[(k8 + 3) * 65 + nn]);
;       o.z = pack2(t[(k8 + 4) * 65 + nn], t[(k8 + 5) * 65 + nn]);
;       o.w = pack2(t[(k8 + 6) * 65 + nn], t[(k8 + 7) * 65 + nn]);
;       const int dn = (!perm_in || n < 5376 || n >= 6160) ? n : (n < 5392 ? n + 768 : n - 16);
;       *(uint4*)(dst + (size_t)dn * K + k0 + k8) = o;
;     }
;   }
; }
; DI void convert_mixer(const PX& p, int l, int tile, float* sm) {
;     ...
;   else cvt_tile(p, p.in[29] + (size_t)l * 768 * 768, W1 + W1_GLU, 768, 768, tile - 8352, sm);
.LBB0_97:
	s_cmpk_gt_i32 s69, 0x1fff
	s_cbranch_scc0 .LBB0_110
	s_add_i32 s70, s69, 0xffffe000
	s_cmpk_gt_u32 s70, 0x181f
	s_cbranch_scc0 .LBB0_111
	s_cmpk_gt_u32 s70, 0x1c1f
	s_cbranch_scc0 .LBB0_112
	s_cmpk_gt_u32 s70, 0x1d9f
	s_cbranch_scc0 .LBB0_113
	s_cmpk_gt_u32 s70, 0x1f1f
	s_cbranch_scc0 .LBB0_114
	s_cmpk_gt_u32 s70, 0x209f
	s_cbranch_scc0 .LBB0_115
	s_and_b32 s24, s1, 0xff
	s_mul_hi_u32 s24, s24, 0x15555556
	s_waitcnt vmcnt(0)
	v_mov_b32_e32 v14, v188
	s_mul_i32 s26, s24, 0xfffffd00
	s_add_i32 s26, s26, s63
	v_lshlrev_b32_e32 v0, 2, v14
	v_and_b32_e32 v0, 60, v0
	s_mul_i32 s24, s69, 0xab
	v_add_u32_e32 v2, s26, v0
	s_add_i32 s24, s24, 0xd520
	v_add_u32_e32 v2, 0xffefd800, v2
	s_lshr_b32 s24, s24, 5
	s_movk_i32 s8, 0x300
	v_ashrrev_i32_e32 v3, 31, v2
	s_and_b32 s71, s24, 0x7c0
	v_cmp_gt_i32_e32 vcc, s8, v2
	s_waitcnt lgkmcnt(0)
	v_lshl_add_u64 v[8:9], v[2:3], 2, s[76:77]
	v_ashrrev_i32_e32 v3, 4, v14
	v_mov_b32_e32 v2, 0
	v_mov_b32_e32 v4, 0
	v_mov_b32_e32 v5, 0
	v_mov_b32_e32 v6, 0
	v_mov_b32_e32 v7, 0
	s_waitcnt lgkmcnt(0)
	s_barrier
	s_and_saveexec_b64 s[24:25], vcc
	s_cbranch_execz .LBB0_105
	v_add_u32_e32 v4, s71, v3
	s_movk_i32 s8, 0xc00
	v_mad_i64_i32 v[4:5], s[60:61], v4, s8, v[8:9]
	v_mov_b32_e32 v200, 0x18000
	v_mov_b32_e32 v201, 0
	v_lshl_add_u64 v[202:203], v[4:5], 0, v[200:201]
	global_load_dwordx4 v[4:7], v[4:5], off
	global_load_dwordx4 v[204:207], v[202:203], off
.LBB0_105:
	s_or_b64 exec, exec, s[24:25]
	v_lshlrev_b32_e32 v0, 2, v0
	s_movk_i32 s8, 0x104
	v_mad_u64_u32 v[10:11], s[24:25], v3, s8, v[0:1]
	v_add_u32_e32 v3, 0x200, v14
	s_waitcnt vmcnt(1)
	ds_write2_b32 v10, v4, v5 offset1:1
	ds_write2_b32 v10, v6, v7 offset0:2 offset1:3
	v_ashrrev_i32_e32 v6, 4, v3
	v_mov_b32_e32 v3, 0
	v_mov_b32_e32 v4, 0
	v_mov_b32_e32 v5, 0
	s_and_saveexec_b64 s[24:25], vcc
	s_cbranch_execz .LBB0_107
	v_add_u32_e32 v2, s71, v6
	s_movk_i32 s8, 0xc00
	v_mad_i64_i32 v[2:3], s[60:61], v2, s8, v[8:9]
	s_waitcnt vmcnt(0)
	v_mov_b32_e32 v2, v204
	v_mov_b32_e32 v3, v205
	v_mov_b32_e32 v4, v206
	v_mov_b32_e32 v5, v207

; #define OPAQUE(x) asm volatile("" : "+v"(x))
; #define TIDX(p) ((p).wv * 64 + (int)__builtin_amdgcn_mbcnt_hi(~0u, __builtin_amdgcn_mbcnt_lo(~0u, 0u)))
; DI unsigned pack2(float a, float b) { f32x2_t v = {a, b}; bf16x2_t r = __builtin_convertvector(v, bf16x2_t); return __builtin_bit_cast(unsigned, r); }
; DI void cvt_tile(const PX& p, const float* __restrict__ src, bfu* __restrict__ dst, int K, int N, int tile, float* t, bool perm_in = false) {
;   const int ntn = (N + 63) >> 6;
;   const int kt = tile / ntn, nt = tile - kt * ntn;
;   const int k0 = kt * 64, n0 = nt * 64;
;   int tidc = TIDX(p); OPAQUE(tidc);
;   __syncthreads();
; #pragma unroll
;   for (int i = 0; i < 2; i++) {
;     const int idx = tidc + i * NTHR;
;     const int kk = idx >> 4, n4 = (idx & 15) * 4, n = n0 + n4;
;     float4 v = make_float4(0.f, 0.f, 0.f, 0.f);
;     if (n < N) v = *(const float4*)(src + (size_t)(k0 + kk) * N + n);
;     t[kk * 65 + n4] = v.x; t[kk * 65 + n4 + 1] = v.y; t[kk * 65 + n4 + 2] = v.z; t[kk * 65 + n4 + 3] = v.w;
;   }
;   __syncthreads();
;   {
;     const int nn = tidc >> 3, k8 = (tidc & 7) * 8, n = n0 + nn;
;     if (n < N) {
;       uint4 o;
;       o.x = pack2(t[(k8 + 0) * 65 + nn], t[(k8 + 1) * 65 + nn]);
;       o.y = pack2(t[(k8 + 2) * 65 + nn], t[(k8 + 3) * 65 + nn]);
;       o.z = pack2(t[(k8 + 4) * 65 + nn], t[(k8 + 5) * 65 + nn]);
;       o.w = pack2(t[(k8 + 6) * 65 + nn], t[(k8 + 7) * 65 + nn]);
;       const int dn = (!perm_in || n < 5376 || n >= 6160) ? n : (n < 5392 ? n + 768 : n - 16);
;       *(uint4*)(dst + (size_t)dn * K + k0 + k8) = o;
;     }
;   }
; }
; DI void convert_mixer(const PX& p, int l, int tile, float* sm) {
;     ...
;   else if (tile < 7200) cvt_tile(p, p.in[34] + (size_t)l * 2048 * 2048, W1 + W1_WOUT, 2048, 2048, tile - 6176, sm);
;   else if (tile < 7584) cvt_tile(p, p.in[31] + (size_t)l * 768 * 2048, W1 + W1_WHY, 768, 2048, tile - 7200, sm);
;   else if (tile < 7968) cvt_tile(p, p.in[32] + (size_t)l * 768 * 2048, W1 + W1_WML, 768, 2048, tile - 7584, sm);
;   else if (tile < 8352) cvt_tile(p, p.in[33] + (size_t)l * 768 * 2048, W1 + W1_WS5, 768, 2048, tile - 7968, sm);
.LBB0_116:
	s_lshl_b32 s26, s2, 6
	s_and_b32 s26, s26, 0xfffff800
	s_waitcnt vmcnt(0)
	v_mov_b32_e32 v14, v188
	s_sub_i32 s61, 0xfff03800, s26
	s_add_i32 s61, s61, s63
	v_lshlrev_b32_e32 v0, 2, v14
	v_and_b32_e32 v0, 60, v0
	s_lshl_b32 s26, s69, 1
	v_add_u32_e32 v2, s61, v0
	s_add_i32 s60, s26, 0xffff81c0
	s_movk_i32 s8, 0x800
	v_ashrrev_i32_e32 v3, 31, v2
	s_andn2_b32 s60, s60, 63
	v_cmp_gt_i32_e32 vcc, s8, v2
	s_waitcnt lgkmcnt(0)
	v_lshl_add_u64 v[8:9], v[2:3], 2, s[38:39]
	v_ashrrev_i32_e32 v3, 4, v14
	v_mov_b32_e32 v2, 0
	v_mov_b32_e32 v4, 0
	v_mov_b32_e32 v5, 0
	v_mov_b32_e32 v6, 0
	v_mov_b32_e32 v7, 0
	s_barrier
	s_and_saveexec_b64 s[26:27], vcc
	s_cbranch_execz .LBB0_118
	v_add_u32_e32 v4, s60, v3
	v_ashrrev_i32_e32 v5, 31, v4
	v_lshlrev_b64 v[4:5], 13, v[4:5]
	v_lshl_add_u64 v[4:5], v[8:9], 0, v[4:5]
	v_mov_b32_e32 v200, 0x40000
	v_mov_b32_e32 v201, 0
	v_lshl_add_u64 v[202:203], v[4:5], 0, v[200:201]
	global_load_dwordx4 v[4:7], v[4:5], off
	global_load_dwordx4 v[204:207], v[202:203], off
.LBB0_118:
	s_or_b64 exec, exec, s[26:27]
	v_lshlrev_b32_e32 v0, 2, v0
	s_movk_i32 s8, 0x104
	v_mad_u64_u32 v[10:11], s[26:27], v3, s8, v[0:1]
	v_add_u32_e32 v3, 0x200, v14
	s_waitcnt vmcnt(1)
	ds_write2_b32 v10, v4, v5 offset1:1
	ds_write2_b32 v10, v6, v7 offset0:2 offset1:3
	v_ashrrev_i32_e32 v6, 4, v3
	v_mov_b32_e32 v3, 0
	v_mov_b32_e32 v4, 0
	v_mov_b32_e32 v5, 0
	s_and_saveexec_b64 s[26:27], vcc
	s_cbranch_execz .LBB0_120
	v_add_u32_e32 v2, s60, v6
	v_ashrrev_i32_e32 v3, 31, v2
	v_lshlrev_b64 v[2:3], 13, v[2:3]
	v_lshl_add_u64 v[2:3], v[8:9], 0, v[2:3]
	s_waitcnt vmcnt(0)
	v_mov_b32_e32 v2, v204
	v_mov_b32_e32 v3, v205
	v_mov_b32_e32 v4, v206
	v_mov_b32_e32 v5, v207

; #define OPAQUE(x) asm volatile("" : "+v"(x))
; #define TIDX(p) ((p).wv * 64 + (int)__builtin_amdgcn_mbcnt_hi(~0u, __builtin_amdgcn_mbcnt_lo(~0u, 0u)))
; DI void cvt_tile(const PX& p, const float* __restrict__ src, bfu* __restrict__ dst, int K, int N, int tile, float* t, bool perm_in = false) {
;   const int ntn = (N + 63) >> 6;
;   const int kt = tile / ntn, nt = tile - kt * ntn;
;   const int k0 = kt * 64, n0 = nt * 64;
;   int tidc = TIDX(p); OPAQUE(tidc);
;   __syncthreads();
; #pragma unroll
;   for (int i = 0; i < 2; i++) {
;     const int idx = tidc + i * NTHR;
;     const int kk = idx >> 4, n4 = (idx & 15) * 4, n = n0 + n4;
;     float4 v = make_float4(0.f, 0.f, 0.f, 0.f);
;     if (n < N) v = *(const float4*)(src + (size_t)(k0 + kk) * N + n);
;     t[kk * 65 + n4] = v.x; t[kk * 65 + n4 + 1] = v.y; t[kk * 65 + n4 + 2] = v.z; t[kk * 65 + n4 + 3] = v.w;
;   }
.LBB0_124:
	s_lshl_b32 s26, s3, 6
	s_and_b32 s26, s26, 0xfffff800
	s_waitcnt vmcnt(0)
	v_mov_b32_e32 v14, v188
	s_sub_i32 s61, 0xfff09800, s26
	s_add_i32 s61, s61, s63
	v_lshlrev_b32_e32 v0, 2, v14
	v_and_b32_e32 v0, 60, v0
	s_lshl_b32 s26, s69, 1
	v_add_u32_e32 v2, s61, v0
	s_add_i32 s60, s26, 0xffff84c0
	s_movk_i32 s8, 0x800
	v_ashrrev_i32_e32 v3, 31, v2
	s_andn2_b32 s60, s60, 63
	v_cmp_gt_i32_e32 vcc, s8, v2
	s_waitcnt lgkmcnt(0)
	v_lshl_add_u64 v[8:9], v[2:3], 2, s[36:37]
	v_ashrrev_i32_e32 v3, 4, v14
	v_mov_b32_e32 v2, 0
	v_mov_b32_e32 v4, 0
	v_mov_b32_e32 v5, 0
	v_mov_b32_e32 v6, 0
	v_mov_b32_e32 v7, 0
	s_barrier
	s_and_saveexec_b64 s[26:27], vcc
	s_cbranch_execz .LBB0_126
	v_add_u32_e32 v4, s60, v3
	v_ashrrev_i32_e32 v5, 31, v4
	v_lshlrev_b64 v[4:5], 13, v[4:5]
	v_lshl_add_u64 v[4:5], v[8:9], 0, v[4:5]
	v_mov_b32_e32 v200, 0x40000
	v_mov_b32_e32 v201, 0
	v_lshl_add_u64 v[202:203], v[4:5], 0, v[200:201]
	global_load_dwordx4 v[4:7], v[4:5], off
	global_load_dwordx4 v[204:207], v[202:203], off

; #define OPAQUE(x) asm volatile("" : "+v"(x))
; #define TIDX(p) ((p).wv * 64 + (int)__builtin_amdgcn_mbcnt_hi(~0u, __builtin_amdgcn_mbcnt_lo(~0u, 0u)))
; DI void cvt_tile(const PX& p, const float* __restrict__ src, bfu* __restrict__ dst, int K, int N, int tile, float* t, bool perm_in = false) {
;   const int ntn = (N + 63) >> 6;
;   const int kt = tile / ntn, nt = tile - kt * ntn;
;   const int k0 = kt * 64, n0 = nt * 64;
;   int tidc = TIDX(p); OPAQUE(tidc);
;   __syncthreads();
; #pragma unroll
;   for (int i = 0; i < 2; i++) {
;     const int idx = tidc + i * NTHR;
;     const int kk = idx >> 4, n4 = (idx & 15) * 4, n = n0 + n4;
;     float4 v = make_float4(0.f, 0.f, 0.f, 0.f);
;     if (n < N) v = *(const float4*)(src + (size_t)(k0 + kk) * N + n);
;     t[kk * 65 + n4] = v.x; t[kk * 65 + n4 + 1] = v.y; t[kk * 65 + n4 + 2] = v.z; t[kk * 65 + n4 + 3] = v.w;
;   }
.LBB0_132:
	s_lshl_b32 s26, s6, 6
	s_and_b32 s26, s26, 0xfffff800
	s_waitcnt vmcnt(0)
	v_mov_b32_e32 v14, v188
	s_sub_i32 s61, 0xfff0f800, s26
	s_add_i32 s61, s61, s63
	v_lshlrev_b32_e32 v0, 2, v14
	v_and_b32_e32 v0, 60, v0
	s_lshl_b32 s26, s69, 1
	v_add_u32_e32 v2, s61, v0
	s_add_i32 s60, s26, 0xffff87c0
	s_movk_i32 s8, 0x800
	v_ashrrev_i32_e32 v3, 31, v2
	s_andn2_b32 s60, s60, 63
	v_cmp_gt_i32_e32 vcc, s8, v2
	s_waitcnt lgkmcnt(0)
	v_lshl_add_u64 v[8:9], v[2:3], 2, s[42:43]
	v_ashrrev_i32_e32 v3, 4, v14
	v_mov_b32_e32 v2, 0
	v_mov_b32_e32 v4, 0
	v_mov_b32_e32 v5, 0
	v_mov_b32_e32 v6, 0
	v_mov_b32_e32 v7, 0
	s_barrier
	s_and_saveexec_b64 s[26:27], vcc
	s_cbranch_execz .LBB0_134
	v_add_u32_e32 v4, s60, v3
	v_ashrrev_i32_e32 v5, 31, v4
	v_lshlrev_b64 v[4:5], 13, v[4:5]
	v_lshl_add_u64 v[4:5], v[8:9], 0, v[4:5]
	v_mov_b32_e32 v200, 0x40000
	v_mov_b32_e32 v201, 0
	v_lshl_add_u64 v[202:203], v[4:5], 0, v[200:201]
	global_load_dwordx4 v[4:7], v[4:5], off
	global_load_dwordx4 v[204:207], v[202:203], off

; #define OPAQUE(x) asm volatile("" : "+v"(x))
; #define TIDX(p) ((p).wv * 64 + (int)__builtin_amdgcn_mbcnt_hi(~0u, __builtin_amdgcn_mbcnt_lo(~0u, 0u)))
; DI unsigned pack2(float a, float b) { f32x2_t v = {a, b}; bf16x2_t r = __builtin_convertvector(v, bf16x2_t); return __builtin_bit_cast(unsigned, r); }
; DI void cvt_tile(const PX& p, const float* __restrict__ src, bfu* __restrict__ dst, int K, int N, int tile, float* t, bool perm_in = false) {
;   const int ntn = (N + 63) >> 6;
;   const int kt = tile / ntn, nt = tile - kt * ntn;
;   const int k0 = kt * 64, n0 = nt * 64;
;   int tidc = TIDX(p); OPAQUE(tidc);
;   __syncthreads();
; #pragma unroll
;   for (int i = 0; i < 2; i++) {
;     const int idx = tidc + i * NTHR;
;     const int kk = idx >> 4, n4 = (idx & 15) * 4, n = n0 + n4;
;     float4 v = make_float4(0.f, 0.f, 0.f, 0.f);
;     if (n < N) v = *(const float4*)(src + (size_t)(k0 + kk) * N + n);
;     t[kk * 65 + n4] = v.x; t[kk * 65 + n4 + 1] = v.y; t[kk * 65 + n4 + 2] = v.z; t[kk * 65 + n4 + 3] = v.w;
;   }
;   __syncthreads();
;   {
;     const int nn = tidc >> 3, k8 = (tidc & 7) * 8, n = n0 + nn;
;     if (n < N) {
;       uint4 o;
;       o.x = pack2(t[(k8 + 0) * 65 + nn], t[(k8 + 1) * 65 + nn]);
;       o.y = pack2(t[(k8 + 2) * 65 + nn], t[(k8 + 3) * 65 + nn]);
;       o.z = pack2(t[(k8 + 4) * 65 + nn], t[(k8 + 5) * 65 + nn]);
;       o.w = pack2(t[(k8 + 6) * 65 + nn], t[(k8 + 7) * 65 + nn]);
;       const int dn = (!perm_in || n < 5376 || n >= 6160) ? n : (n < 5392 ? n + 768 : n - 16);
;       *(uint4*)(dst + (size_t)dn * K + k0 + k8) = o;
;     }
;   }
; }
; DI void convert_mixer(const PX& p, int l, int tile, float* sm) {
;     ...
;   else if (tile < 7200) cvt_tile(p, p.in[34] + (size_t)l * 2048 * 2048, W1 + W1_WOUT, 2048, 2048, tile - 6176, sm);
;   else if (tile < 7584) cvt_tile(p, p.in[31] + (size_t)l * 768 * 2048, W1 + W1_WHY, 768, 2048, tile - 7200, sm);
;   else if (tile < 7968) cvt_tile(p, p.in[32] + (size_t)l * 768 * 2048, W1 + W1_WML, 768, 2048, tile - 7584, sm);
;   else if (tile < 8352) cvt_tile(p, p.in[33] + (size_t)l * 768 * 2048, W1 + W1_WS5, 768, 2048, tile - 7968, sm);
.LBB0_140:
	s_lshl_b32 s26, s7, 6
	s_and_b32 s26, s26, 0xfffff800
	s_waitcnt vmcnt(0)
	v_mov_b32_e32 v15, v188
	s_sub_i32 s61, 0xfff1f800, s26
	s_add_i32 s61, s61, s63
	v_lshlrev_b32_e32 v0, 2, v15
	v_and_b32_e32 v0, 60, v0
	s_lshl_b32 s26, s69, 1
	v_add_u32_e32 v2, s61, v0
	s_add_i32 s60, s26, 0xffff8fc0
	s_movk_i32 s8, 0x800
	v_ashrrev_i32_e32 v3, 31, v2
	s_andn2_b32 s60, s60, 63
	v_cmp_gt_i32_e32 vcc, s8, v2
	s_waitcnt lgkmcnt(0)
	v_lshl_add_u64 v[8:9], v[2:3], 2, s[40:41]
	v_ashrrev_i32_e32 v3, 4, v15
	v_mov_b32_e32 v2, 0
	v_mov_b32_e32 v4, 0
	v_mov_b32_e32 v5, 0
	v_mov_b32_e32 v6, 0
	v_mov_b32_e32 v7, 0
	s_barrier
	s_and_saveexec_b64 s[26:27], vcc
	s_cbranch_execz .LBB0_142
	v_add_u32_e32 v4, s60, v3
	v_ashrrev_i32_e32 v5, 31, v4
	v_lshlrev_b64 v[4:5], 13, v[4:5]
	v_lshl_add_u64 v[4:5], v[8:9], 0, v[4:5]
	v_mov_b32_e32 v200, 0x40000
	v_mov_b32_e32 v201, 0
	v_lshl_add_u64 v[202:203], v[4:5], 0, v[200:201]
	global_load_dwordx4 v[4:7], v[4:5], off
	global_load_dwordx4 v[204:207], v[202:203], off
.LBB0_142:
	s_or_b64 exec, exec, s[26:27]
	v_lshlrev_b32_e32 v0, 2, v0
	s_movk_i32 s8, 0x104
	v_mad_u64_u32 v[10:11], s[26:27], v3, s8, v[0:1]
	v_add_u32_e32 v3, 0x200, v15
	s_waitcnt vmcnt(1)
	ds_write2_b32 v10, v4, v5 offset1:1
	ds_write2_b32 v10, v6, v7 offset0:2 offset1:3
	v_ashrrev_i32_e32 v6, 4, v3
	v_mov_b32_e32 v3, 0
	v_mov_b32_e32 v4, 0
	v_mov_b32_e32 v5, 0
	s_and_saveexec_b64 s[26:27], vcc
	s_cbranch_execz .LBB0_144
	v_add_u32_e32 v2, s60, v6
	v_ashrrev_i32_e32 v3, 31, v2
	v_lshlrev_b64 v[2:3], 13, v[2:3]
	v_lshl_add_u64 v[2:3], v[8:9], 0, v[2:3]
	s_waitcnt vmcnt(0)
	v_mov_b32_e32 v2, v204
	v_mov_b32_e32 v3, v205
	v_mov_b32_e32 v4, v206
	v_mov_b32_e32 v5, v207

; #define OPAQUE(x) asm volatile("" : "+v"(x))
; #define TIDX(p) ((p).wv * 64 + (int)__builtin_amdgcn_mbcnt_hi(~0u, __builtin_amdgcn_mbcnt_lo(~0u, 0u)))
; DI unsigned pack2(float a, float b) { f32x2_t v = {a, b}; bf16x2_t r = __builtin_convertvector(v, bf16x2_t); return __builtin_bit_cast(unsigned, r); }
; DI void cvt_tile(const PX& p, const float* __restrict__ src, bfu* __restrict__ dst, int K, int N, int tile, float* t, bool perm_in = false) {
;   const int ntn = (N + 63) >> 6;
;   const int kt = tile / ntn, nt = tile - kt * ntn;
;   const int k0 = kt * 64, n0 = nt * 64;
;   int tidc = TIDX(p); OPAQUE(tidc);
;   __syncthreads();
; #pragma unroll
;   for (int i = 0; i < 2; i++) {
;     const int idx = tidc + i * NTHR;
;     const int kk = idx >> 4, n4 = (idx & 15) * 4, n = n0 + n4;
;     float4 v = make_float4(0.f, 0.f, 0.f, 0.f);
;     if (n < N) v = *(const float4*)(src + (size_t)(k0 + kk) * N + n);
;     t[kk * 65 + n4] = v.x; t[kk * 65 + n4 + 1] = v.y; t[kk * 65 + n4 + 2] = v.z; t[kk * 65 + n4 + 3] = v.w;
;   }
;   __syncthreads();
;   {
;     const int nn = tidc >> 3, k8 = (tidc & 7) * 8, n = n0 + nn;
;     if (n < N) {
;       uint4 o;
;       o.x = pack2(t[(k8 + 0) * 65 + nn], t[(k8 + 1) * 65 + nn]);
;       o.y = pack2(t[(k8 + 2) * 65 + nn], t[(k8 + 3) * 65 + nn]);
;       o.z = pack2(t[(k8 + 4) * 65 + nn], t[(k8 + 5) * 65 + nn]);
;       o.w = pack2(t[(k8 + 6) * 65 + nn], t[(k8 + 7) * 65 + nn]);
;       const int dn = (!perm_in || n < 5376 || n >= 6160) ? n : (n < 5392 ? n + 768 : n - 16);
;       *(uint4*)(dst + (size_t)dn * K + k0 + k8) = o;
;     }
;   }
; }
; DI void convert_mixer(const PX& p, int l, int tile, float* sm) {
;     ...
;   if (tile < 6176) cvt_tile(p, p.in[6] + (size_t)l * 2048 * NIN, W1 + W1_WIN, 2048, NIN, tile, sm, true);
.LBB0_148:
	s_and_b32 s26, 0xffff, s62
	s_mul_hi_u32 s26, s26, 0x1539095
	s_mulk_i32 s26, 0x3040
	s_sub_i32 s61, 0xfff7eb00, s26
	s_mul_i32 s26, s70, 0x5391
	s_waitcnt vmcnt(0)
	v_mov_b32_e32 v14, v188
	s_lshr_b32 s26, s26, 16
	s_sub_i32 s27, s70, s26
	v_lshlrev_b32_e32 v0, 2, v14
	v_and_b32_e32 v0, 60, v0
	s_add_i32 s61, s61, s63
	s_bfe_u32 s27, s27, 0xf0001
	v_add_u32_e32 v2, s61, v0
	s_add_i32 s27, s27, s26
	v_add_u32_e32 v2, 0x1500, v2
	s_lshr_b32 s26, s27, 1
	s_movk_i32 s8, 0x3010
	v_ashrrev_i32_e32 v3, 31, v2
	s_and_b32 s60, s26, 0x7fc0
	v_cmp_gt_i32_e32 vcc, s8, v2
	s_waitcnt lgkmcnt(0)
	v_lshl_add_u64 v[8:9], v[2:3], 2, s[4:5]
	v_ashrrev_i32_e32 v3, 4, v14
	v_mov_b32_e32 v2, 0
	v_mov_b32_e32 v4, 0
	v_mov_b32_e32 v5, 0
	v_mov_b32_e32 v6, 0
	v_mov_b32_e32 v7, 0
	s_barrier
	s_and_saveexec_b64 s[26:27], vcc
	s_cbranch_execz .LBB0_150
	v_add_u32_e32 v4, s60, v3
	s_mov_b32 s8, 0xc040
	v_mad_i64_i32 v[4:5], s[70:71], v4, s8, v[8:9]
	v_mov_b32_e32 v200, 0x180800
	v_mov_b32_e32 v201, 0
	v_lshl_add_u64 v[202:203], v[4:5], 0, v[200:201]
	global_load_dwordx4 v[4:7], v[4:5], off
	global_load_dwordx4 v[204:207], v[202:203], off
.LBB0_150:
	s_or_b64 exec, exec, s[26:27]
	v_lshlrev_b32_e32 v0, 2, v0
	s_movk_i32 s8, 0x104
	v_mad_u64_u32 v[10:11], s[26:27], v3, s8, v[0:1]
	v_add_u32_e32 v3, 0x200, v14
	s_waitcnt vmcnt(1)
	ds_write2_b32 v10, v4, v5 offset1:1
	ds_write2_b32 v10, v6, v7 offset0:2 offset1:3
	v_ashrrev_i32_e32 v6, 4, v3
	v_mov_b32_e32 v3, 0
	v_mov_b32_e32 v4, 0
	v_mov_b32_e32 v5, 0
	s_and_saveexec_b64 s[26:27], vcc
	s_cbranch_execz .LBB0_152
	v_add_u32_e32 v2, s60, v6
	s_mov_b32 s8, 0xc040
	v_mad_i64_i32 v[2:3], s[70:71], v2, s8, v[8:9]
	s_waitcnt vmcnt(0)
	v_mov_b32_e32 v2, v204
	v_mov_b32_e32 v3, v205
	v_mov_b32_e32 v4, v206
	v_mov_b32_e32 v5, v207

; #define OPAQUE(x) asm volatile("" : "+v"(x))
; #define TIDX(p) ((p).wv * 64 + (int)__builtin_amdgcn_mbcnt_hi(~0u, __builtin_amdgcn_mbcnt_lo(~0u, 0u)))
; DI unsigned pack2(float a, float b) { f32x2_t v = {a, b}; bf16x2_t r = __builtin_convertvector(v, bf16x2_t); return __builtin_bit_cast(unsigned, r); }
; DI void cvt_tile(const PX& p, const float* __restrict__ src, bfu* __restrict__ dst, int K, int N, int tile, float* t, bool perm_in = false) {
;   const int ntn = (N + 63) >> 6;
;   const int kt = tile / ntn, nt = tile - kt * ntn;
;   const int k0 = kt * 64, n0 = nt * 64;
;   int tidc = TIDX(p); OPAQUE(tidc);
;   __syncthreads();
; #pragma unroll
;   for (int i = 0; i < 2; i++) {
;     const int idx = tidc + i * NTHR;
;     const int kk = idx >> 4, n4 = (idx & 15) * 4, n = n0 + n4;
;     float4 v = make_float4(0.f, 0.f, 0.f, 0.f);
;     if (n < N) v = *(const float4*)(src + (size_t)(k0 + kk) * N + n);
;     t[kk * 65 + n4] = v.x; t[kk * 65 + n4 + 1] = v.y; t[kk * 65 + n4 + 2] = v.z; t[kk * 65 + n4 + 3] = v.w;
;   }
;   __syncthreads();
;   {
;     const int nn = tidc >> 3, k8 = (tidc & 7) * 8, n = n0 + nn;
;     if (n < N) {
;       uint4 o;
;       o.x = pack2(t[(k8 + 0) * 65 + nn], t[(k8 + 1) * 65 + nn]);
;       o.y = pack2(t[(k8 + 2) * 65 + nn], t[(k8 + 3) * 65 + nn]);
;       o.z = pack2(t[(k8 + 4) * 65 + nn], t[(k8 + 5) * 65 + nn]);
;       o.w = pack2(t[(k8 + 6) * 65 + nn], t[(k8 + 7) * 65 + nn]);
;       const int dn = (!perm_in || n < 5376 || n >= 6160) ? n : (n < 5392 ? n + 768 : n - 16);
;       *(uint4*)(dst + (size_t)dn * K + k0 + k8) = o;
;     }
;   }
; }
; DI void convert_ffn(const PX& p, int l, int tile, float* sm) {
;     ...
;   else cvt_tile(p, p.in[40] + (size_t)l * 8192 * 2048, W2 + (size_t)8192 * 2048, 8192, 2048, tile - 4096, sm);
.LBB0_158:
	s_cmpk_gt_i32 s69, 0xfff
	s_mov_b64 s[24:25], -1
	s_cbranch_scc0 .LBB0_166
	s_lshl_b32 s24, s68, 6
	s_and_b32 s60, s24, 0xfffff800
	s_lshl_b32 s24, s69, 1
	s_waitcnt vmcnt(0)
	v_mov_b32_e32 v13, v188
	s_addk_i32 s24, 0xe000
	v_readlane_b32 s8, v253, 31
	s_and_b32 s8, s24, 0xffffffc0
	v_lshlrev_b32_e32 v0, 2, v13
	v_and_b32_e32 v0, 60, v0
	s_sub_i32 s24, s63, s60
	v_readlane_b32 s9, v253, 32
	v_add_u32_e32 v2, s24, v0
	v_writelane_b32 v253, s8, 31
	v_add_u32_e32 v2, 0xfffc0000, v2
	v_ashrrev_i32_e32 v3, 31, v2
	v_writelane_b32 v253, s9, 32
	s_movk_i32 s8, 0x800
	v_cmp_gt_i32_e32 vcc, s8, v2
	s_waitcnt lgkmcnt(0)
	v_lshl_add_u64 v[8:9], v[2:3], 2, s[20:21]
	v_ashrrev_i32_e32 v3, 4, v13
	v_mov_b32_e32 v2, 0
	v_mov_b32_e32 v4, 0
	v_mov_b32_e32 v5, 0
	v_mov_b32_e32 v6, 0
	v_mov_b32_e32 v7, 0
	s_barrier
	s_and_saveexec_b64 s[24:25], vcc
	s_cbranch_execz .LBB0_161
	v_readlane_b32 s8, v253, 31
	v_readlane_b32 s9, v253, 32
	s_nop 0
	v_add_u32_e32 v4, s8, v3
	v_ashrrev_i32_e32 v5, 31, v4
	v_lshlrev_b64 v[4:5], 13, v[4:5]
	v_lshl_add_u64 v[4:5], v[8:9], 0, v[4:5]
	v_mov_b32_e32 v200, 0x40000
	v_mov_b32_e32 v201, 0
	v_lshl_add_u64 v[202:203], v[4:5], 0, v[200:201]
	global_load_dwordx4 v[4:7], v[4:5], off
	global_load_dwordx4 v[204:207], v[202:203], off
.LBB0_161:
	s_or_b64 exec, exec, s[24:25]
	v_lshlrev_b32_e32 v0, 2, v0
	s_movk_i32 s8, 0x104
	v_mad_u64_u32 v[10:11], s[24:25], v3, s8, v[0:1]
	v_add_u32_e32 v3, 0x200, v13
	s_waitcnt vmcnt(1)
	ds_write2_b32 v10, v4, v5 offset1:1
	ds_write2_b32 v10, v6, v7 offset0:2 offset1:3
	v_ashrrev_i32_e32 v6, 4, v3
	v_mov_b32_e32 v3, 0
	v_mov_b32_e32 v4, 0
	v_mov_b32_e32 v5, 0
	s_and_saveexec_b64 s[24:25], vcc
	s_cbranch_execz .LBB0_163
	v_readlane_b32 s8, v253, 31
	v_readlane_b32 s9, v253, 32
	s_nop 0
	v_add_u32_e32 v2, s8, v6
	v_ashrrev_i32_e32 v3, 31, v2
	v_lshlrev_b64 v[2:3], 13, v[2:3]
	v_lshl_add_u64 v[2:3], v[8:9], 0, v[2:3]
	s_waitcnt vmcnt(0)
	v_mov_b32_e32 v2, v204
	v_mov_b32_e32 v3, v205
	v_mov_b32_e32 v4, v206
	v_mov_b32_e32 v5, v207

; #define OPAQUE(x) asm volatile("" : "+v"(x))
; #define TIDX(p) ((p).wv * 64 + (int)__builtin_amdgcn_mbcnt_hi(~0u, __builtin_amdgcn_mbcnt_lo(~0u, 0u)))
; DI unsigned pack2(float a, float b) { f32x2_t v = {a, b}; bf16x2_t r = __builtin_convertvector(v, bf16x2_t); return __builtin_bit_cast(unsigned, r); }
; DI void cvt_tile(const PX& p, const float* __restrict__ src, bfu* __restrict__ dst, int K, int N, int tile, float* t, bool perm_in = false) {
;   const int ntn = (N + 63) >> 6;
;   const int kt = tile / ntn, nt = tile - kt * ntn;
;   const int k0 = kt * 64, n0 = nt * 64;
;   int tidc = TIDX(p); OPAQUE(tidc);
;   __syncthreads();
; #pragma unroll
;   for (int i = 0; i < 2; i++) {
;     const int idx = tidc + i * NTHR;
;     const int kk = idx >> 4, n4 = (idx & 15) * 4, n = n0 + n4;
;     float4 v = make_float4(0.f, 0.f, 0.f, 0.f);
;     if (n < N) v = *(const float4*)(src + (size_t)(k0 + kk) * N + n);
;     t[kk * 65 + n4] = v.x; t[kk * 65 + n4 + 1] = v.y; t[kk * 65 + n4 + 2] = v.z; t[kk * 65 + n4 + 3] = v.w;
;   }
;   __syncthreads();
;   {
;     const int nn = tidc >> 3, k8 = (tidc & 7) * 8, n = n0 + nn;
;     if (n < N) {
;       uint4 o;
;       o.x = pack2(t[(k8 + 0) * 65 + nn], t[(k8 + 1) * 65 + nn]);
;       o.y = pack2(t[(k8 + 2) * 65 + nn], t[(k8 + 3) * 65 + nn]);
;       o.z = pack2(t[(k8 + 4) * 65 + nn], t[(k8 + 5) * 65 + nn]);
;       o.w = pack2(t[(k8 + 6) * 65 + nn], t[(k8 + 7) * 65 + nn]);
;       const int dn = (!perm_in || n < 5376 || n >= 6160) ? n : (n < 5392 ? n + 768 : n - 16);
;       *(uint4*)(dst + (size_t)dn * K + k0 + k8) = o;
;     }
;   }
; }
; DI void convert_ffn(const PX& p, int l, int tile, float* sm) {
;     ...
;   if (tile < 4096) cvt_tile(p, p.in[39] + (size_t)l * 2048 * 8192, W2, 2048, 8192, tile, sm);
.LBB0_166:
	s_and_b64 vcc, exec, s[24:25]
	s_cbranch_vccz .LBB0_174
	s_ashr_i32 s24, s69, 31
	s_lshr_b32 s24, s24, 25
	s_add_i32 s24, s69, s24
	s_waitcnt vmcnt(0)
	v_mov_b32_e32 v13, v188
	s_ashr_i32 s25, s24, 7
	s_lshl_b32 s24, s25, 6
	v_lshlrev_b32_e32 v0, 2, v13
	s_lshl_b32 s25, s25, 13
	v_and_b32_e32 v0, 60, v0
	v_subrev_u32_e32 v2, s25, v0
	v_add_u32_e32 v2, s63, v2
	s_movk_i32 s8, 0x2000
	v_ashrrev_i32_e32 v3, 31, v2
	v_cmp_gt_i32_e32 vcc, s8, v2
	s_waitcnt lgkmcnt(0)
	v_lshl_add_u64 v[8:9], v[2:3], 2, s[22:23]
	v_ashrrev_i32_e32 v3, 4, v13
	v_mov_b32_e32 v2, 0
	v_mov_b32_e32 v4, 0
	v_mov_b32_e32 v5, 0
	v_mov_b32_e32 v6, 0
	v_mov_b32_e32 v7, 0
	s_barrier
	s_and_saveexec_b64 s[60:61], vcc
	s_cbranch_execz .LBB0_169
	v_add_u32_e32 v4, s24, v3
	v_ashrrev_i32_e32 v5, 31, v4
	v_lshlrev_b64 v[4:5], 15, v[4:5]
	v_lshl_add_u64 v[4:5], v[8:9], 0, v[4:5]
	v_mov_b32_e32 v200, 0x100000
	v_mov_b32_e32 v201, 0
	v_lshl_add_u64 v[202:203], v[4:5], 0, v[200:201]
	global_load_dwordx4 v[4:7], v[4:5], off
	global_load_dwordx4 v[204:207], v[202:203], off
.LBB0_169:
	s_or_b64 exec, exec, s[60:61]
	v_lshlrev_b32_e32 v0, 2, v0
	s_movk_i32 s8, 0x104
	v_mad_u64_u32 v[10:11], s[60:61], v3, s8, v[0:1]
	v_add_u32_e32 v3, 0x200, v13
	s_waitcnt vmcnt(1)
	ds_write2_b32 v10, v4, v5 offset1:1
	ds_write2_b32 v10, v6, v7 offset0:2 offset1:3
	v_ashrrev_i32_e32 v6, 4, v3
	v_mov_b32_e32 v3, 0
	v_mov_b32_e32 v4, 0
	v_mov_b32_e32 v5, 0
	s_and_saveexec_b64 s[60:61], vcc
	s_cbranch_execz .LBB0_171
	v_add_u32_e32 v2, s24, v6
	v_ashrrev_i32_e32 v3, 31, v2
	v_lshlrev_b64 v[2:3], 15, v[2:3]
	v_lshl_add_u64 v[2:3], v[8:9], 0, v[2:3]
	s_waitcnt vmcnt(0)
	v_mov_b32_e32 v2, v204
	v_mov_b32_e32 v3, v205
	v_mov_b32_e32 v4, v206
	v_mov_b32_e32 v5, v207

; #define OPAQUE(x) asm volatile("" : "+v"(x))
; #define TIDX(p) ((p).wv * 64 + (int)__builtin_amdgcn_mbcnt_hi(~0u, __builtin_amdgcn_mbcnt_lo(~0u, 0u)))
; DI unsigned pack2(float a, float b) { f32x2_t v = {a, b}; bf16x2_t r = __builtin_convertvector(v, bf16x2_t); return __builtin_bit_cast(unsigned, r); }
; DI void cvt_tile(const PX& p, const float* __restrict__ src, bfu* __restrict__ dst, int K, int N, int tile, float* t, bool perm_in = false) {
;   const int ntn = (N + 63) >> 6;
;   const int kt = tile / ntn, nt = tile - kt * ntn;
;   const int k0 = kt * 64, n0 = nt * 64;
;   int tidc = TIDX(p); OPAQUE(tidc);
;   __syncthreads();
; #pragma unroll
;   for (int i = 0; i < 2; i++) {
;     const int idx = tidc + i * NTHR;
;     const int kk = idx >> 4, n4 = (idx & 15) * 4, n = n0 + n4;
;     float4 v = make_float4(0.f, 0.f, 0.f, 0.f);
;     if (n < N) v = *(const float4*)(src + (size_t)(k0 + kk) * N + n);
;     t[kk * 65 + n4] = v.x; t[kk * 65 + n4 + 1] = v.y; t[kk * 65 + n4 + 2] = v.z; t[kk * 65 + n4 + 3] = v.w;
;   }
;   __syncthreads();
;   {
;     const int nn = tidc >> 3, k8 = (tidc & 7) * 8, n = n0 + nn;
;     if (n < N) {
;       uint4 o;
;       o.x = pack2(t[(k8 + 0) * 65 + nn], t[(k8 + 1) * 65 + nn]);
;       o.y = pack2(t[(k8 + 2) * 65 + nn], t[(k8 + 3) * 65 + nn]);
;       o.z = pack2(t[(k8 + 4) * 65 + nn], t[(k8 + 5) * 65 + nn]);
;       o.w = pack2(t[(k8 + 6) * 65 + nn], t[(k8 + 7) * 65 + nn]);
;       const int dn = (!perm_in || n < 5376 || n >= 6160) ? n : (n < 5392 ? n + 768 : n - 16);
;       *(uint4*)(dst + (size_t)dn * K + k0 + k8) = o;
;     }
;   }
; }
; DI void convert_mixer(const PX& p, int l, int tile, float* sm) {
;     ...
;   else cvt_tile(p, p.in[29] + (size_t)l * 768 * 768, W1 + W1_GLU, 768, 768, tile - 8352, sm);
; DI void phase0(const PX& p, unsigned char* smem) {
;     ...
;     else convert_mixer(p, 0, it - n_mod - N_FILT_ITEMS, sm);
.LBB0_798:
	s_cmpk_gt_i32 s1, 0x17f
	s_mov_b64 s[4:5], -1
	s_cbranch_scc0 .LBB0_812
	s_cmpk_gt_u32 s1, 0x39f
	s_cbranch_scc0 .LBB0_860
	s_add_i32 s0, s1, 0xfffffc60
	s_cmpk_gt_u32 s0, 0x181f
	s_cbranch_scc0 .LBB0_813
	s_cmpk_gt_u32 s0, 0x1c1f
	s_cbranch_scc0 .LBB0_814
	s_cmpk_gt_u32 s0, 0x1d9f
	s_cbranch_scc0 .LBB0_815
	s_cmpk_gt_u32 s0, 0x1f1f
	s_cbranch_scc0 .LBB0_816
	s_cmpk_gt_u32 s0, 0x209f
	s_cbranch_scc0 .LBB0_817
	s_add_i32 s2, s1, 0xffffdbc0
	s_mul_i32 s3, s2, 0xab
	s_bfe_u32 s3, s3, 0x5000b
	s_mul_i32 s4, s3, -12
	s_waitcnt vmcnt(0)
	v_mov_b32_e32 v14, v188
	s_add_i32 s4, s4, s2
	s_lshl_b32 s2, s3, 6
	v_lshlrev_b32_e32 v0, 2, v14
	s_lshl_b32 s3, s4, 6
	v_and_b32_e32 v0, 60, v0
	v_or_b32_e32 v2, s3, v0
	s_movk_i32 s4, 0x300
	v_cmp_gt_i32_e32 vcc, s4, v2
	v_readlane_b32 s4, v252, 51
	v_ashrrev_i32_e32 v3, 31, v2
	v_readlane_b32 s14, v252, 61
	v_readlane_b32 s15, v252, 62
	v_readlane_b32 s5, v252, 52
	s_waitcnt lgkmcnt(0)
	v_mov_b32_e32 v4, 0
	v_lshl_add_u64 v[8:9], v[2:3], 2, s[14:15]
	v_ashrrev_i32_e32 v3, 4, v14
	v_mov_b32_e32 v2, 0
	v_mov_b32_e32 v5, 0
	v_mov_b32_e32 v6, 0
	v_mov_b32_e32 v7, 0
	s_barrier
	v_readlane_b32 s6, v252, 53
	v_readlane_b32 s7, v252, 54
	v_readlane_b32 s8, v252, 55
	v_readlane_b32 s9, v252, 56
	v_readlane_b32 s10, v252, 57
	v_readlane_b32 s11, v252, 58
	v_readlane_b32 s12, v252, 59
	v_readlane_b32 s13, v252, 60
	v_readlane_b32 s16, v252, 63
	v_readlane_b32 s17, v253, 0
	v_readlane_b32 s18, v253, 1
	v_readlane_b32 s19, v253, 2
	s_and_saveexec_b64 s[4:5], vcc
	s_cbranch_execz .LBB0_807
	v_add_u32_e32 v4, s2, v3
	s_movk_i32 s6, 0xc00
	v_mad_i64_i32 v[4:5], s[6:7], v4, s6, v[8:9]
	v_mov_b32_e32 v200, 0x18000
	v_mov_b32_e32 v201, 0
	v_lshl_add_u64 v[202:203], v[4:5], 0, v[200:201]
	global_load_dwordx4 v[4:7], v[4:5], off
	global_load_dwordx4 v[204:207], v[202:203], off
.LBB0_807:
	s_or_b64 exec, exec, s[4:5]
	v_lshlrev_b32_e32 v0, 2, v0
	s_movk_i32 s4, 0x104
	v_mad_u64_u32 v[10:11], s[4:5], v3, s4, v[0:1]
	v_add_u32_e32 v3, 0x200, v14
	s_waitcnt vmcnt(1)
	ds_write2_b32 v10, v4, v5 offset1:1
	ds_write2_b32 v10, v6, v7 offset0:2 offset1:3
	v_ashrrev_i32_e32 v6, 4, v3
	v_mov_b32_e32 v3, 0
	v_mov_b32_e32 v4, 0
	v_mov_b32_e32 v5, 0
	s_and_saveexec_b64 s[4:5], vcc
	s_cbranch_execz .LBB0_809
	v_add_u32_e32 v2, s2, v6
	s_movk_i32 s6, 0xc00
	v_mad_i64_i32 v[2:3], s[6:7], v2, s6, v[8:9]
	s_waitcnt vmcnt(0)
	v_mov_b32_e32 v2, v204
	v_mov_b32_e32 v3, v205
	v_mov_b32_e32 v4, v206
	v_mov_b32_e32 v5, v207

; #define OPAQUE(x) asm volatile("" : "+v"(x))
; #define TIDX(p) ((p).wv * 64 + (int)__builtin_amdgcn_mbcnt_hi(~0u, __builtin_amdgcn_mbcnt_lo(~0u, 0u)))
; DI unsigned pack2(float a, float b) { f32x2_t v = {a, b}; bf16x2_t r = __builtin_convertvector(v, bf16x2_t); return __builtin_bit_cast(unsigned, r); }
; DI void cvt_tile(const PX& p, const float* __restrict__ src, bfu* __restrict__ dst, int K, int N, int tile, float* t, bool perm_in = false) {
;   const int ntn = (N + 63) >> 6;
;   const int kt = tile / ntn, nt = tile - kt * ntn;
;   const int k0 = kt * 64, n0 = nt * 64;
;   int tidc = TIDX(p); OPAQUE(tidc);
;   __syncthreads();
; #pragma unroll
;   for (int i = 0; i < 2; i++) {
;     const int idx = tidc + i * NTHR;
;     const int kk = idx >> 4, n4 = (idx & 15) * 4, n = n0 + n4;
;     float4 v = make_float4(0.f, 0.f, 0.f, 0.f);
;     if (n < N) v = *(const float4*)(src + (size_t)(k0 + kk) * N + n);
;     t[kk * 65 + n4] = v.x; t[kk * 65 + n4 + 1] = v.y; t[kk * 65 + n4 + 2] = v.z; t[kk * 65 + n4 + 3] = v.w;
;   }
;   __syncthreads();
;   {
;     const int nn = tidc >> 3, k8 = (tidc & 7) * 8, n = n0 + nn;
;     if (n < N) {
;       uint4 o;
;       o.x = pack2(t[(k8 + 0) * 65 + nn], t[(k8 + 1) * 65 + nn]);
;       o.y = pack2(t[(k8 + 2) * 65 + nn], t[(k8 + 3) * 65 + nn]);
;       o.z = pack2(t[(k8 + 4) * 65 + nn], t[(k8 + 5) * 65 + nn]);
;       o.w = pack2(t[(k8 + 6) * 65 + nn], t[(k8 + 7) * 65 + nn]);
;       const int dn = (!perm_in || n < 5376 || n >= 6160) ? n : (n < 5392 ? n + 768 : n - 16);
;       *(uint4*)(dst + (size_t)dn * K + k0 + k8) = o;
;     }
;   }
; }
; DI void convert_mixer(const PX& p, int l, int tile, float* sm) {
;     ...
;   else if (tile < 7584) cvt_tile(p, p.in[31] + (size_t)l * 768 * 2048, W1 + W1_WHY, 768, 2048, tile - 7200, sm);
;   else if (tile < 7968) cvt_tile(p, p.in[32] + (size_t)l * 768 * 2048, W1 + W1_WML, 768, 2048, tile - 7584, sm);
;   else if (tile < 8352) cvt_tile(p, p.in[33] + (size_t)l * 768 * 2048, W1 + W1_WS5, 768, 2048, tile - 7968, sm);
.LBB0_818:
	s_add_i32 s3, s1, 0xffffdd40
	s_lshr_b32 s6, s3, 5
	s_waitcnt vmcnt(0)
	v_mov_b32_e32 v14, v188
	s_lshl_b32 s2, s6, 6
	s_lshl_b32 s6, s6, 11
	s_lshl_b32 s3, s3, 6
	s_sub_i32 s3, s3, s6
	v_lshlrev_b32_e32 v0, 2, v14
	v_and_b32_e32 v0, 60, v0
	v_or_b32_e32 v2, s3, v0
	v_readlane_b32 s8, v253, 3
	s_movk_i32 s6, 0x800
	v_ashrrev_i32_e32 v3, 31, v2
	v_readlane_b32 s10, v253, 5
	v_readlane_b32 s11, v253, 6
	v_cmp_gt_i32_e32 vcc, s6, v2
	s_waitcnt lgkmcnt(0)
	v_mov_b32_e32 v4, 0
	v_lshl_add_u64 v[8:9], v[2:3], 2, s[10:11]
	v_ashrrev_i32_e32 v3, 4, v14
	v_mov_b32_e32 v2, 0
	v_mov_b32_e32 v5, 0
	v_mov_b32_e32 v6, 0
	v_mov_b32_e32 v7, 0
	s_barrier
	v_readlane_b32 s9, v253, 4
	v_readlane_b32 s12, v253, 7
	v_readlane_b32 s13, v253, 8
	v_readlane_b32 s14, v253, 9
	v_readlane_b32 s15, v253, 10
	v_readlane_b32 s16, v253, 11
	v_readlane_b32 s17, v253, 12
	v_readlane_b32 s18, v253, 13
	v_readlane_b32 s19, v253, 14
	v_readlane_b32 s20, v253, 15
	v_readlane_b32 s21, v253, 16
	v_readlane_b32 s22, v253, 17
	v_readlane_b32 s23, v253, 18
	s_and_saveexec_b64 s[6:7], vcc
	s_cbranch_execz .LBB0_820
	v_add_u32_e32 v4, s2, v3
	v_ashrrev_i32_e32 v5, 31, v4
	v_lshlrev_b64 v[4:5], 13, v[4:5]
	v_lshl_add_u64 v[4:5], v[8:9], 0, v[4:5]
	v_mov_b32_e32 v200, 0x40000
	v_mov_b32_e32 v201, 0
	v_lshl_add_u64 v[202:203], v[4:5], 0, v[200:201]
	global_load_dwordx4 v[4:7], v[4:5], off
	global_load_dwordx4 v[204:207], v[202:203], off
.LBB0_820:
	s_or_b64 exec, exec, s[6:7]
	v_lshlrev_b32_e32 v0, 2, v0
	s_movk_i32 s6, 0x104
	v_mad_u64_u32 v[10:11], s[6:7], v3, s6, v[0:1]
	v_add_u32_e32 v3, 0x200, v14
	s_waitcnt vmcnt(1)
	ds_write2_b32 v10, v4, v5 offset1:1
	ds_write2_b32 v10, v6, v7 offset0:2 offset1:3
	v_ashrrev_i32_e32 v6, 4, v3
	v_mov_b32_e32 v3, 0
	v_mov_b32_e32 v4, 0
	v_mov_b32_e32 v5, 0
	s_and_saveexec_b64 s[6:7], vcc
	s_cbranch_execz .LBB0_822
	v_add_u32_e32 v2, s2, v6
	v_ashrrev_i32_e32 v3, 31, v2
	v_lshlrev_b64 v[2:3], 13, v[2:3]
	v_lshl_add_u64 v[2:3], v[8:9], 0, v[2:3]
	s_waitcnt vmcnt(0)
	v_mov_b32_e32 v2, v204
	v_mov_b32_e32 v3, v205
	v_mov_b32_e32 v4, v206
	v_mov_b32_e32 v5, v207

; #define OPAQUE(x) asm volatile("" : "+v"(x))
; #define TIDX(p) ((p).wv * 64 + (int)__builtin_amdgcn_mbcnt_hi(~0u, __builtin_amdgcn_mbcnt_lo(~0u, 0u)))
; DI void cvt_tile(const PX& p, const float* __restrict__ src, bfu* __restrict__ dst, int K, int N, int tile, float* t, bool perm_in = false) {
;   const int ntn = (N + 63) >> 6;
;   const int kt = tile / ntn, nt = tile - kt * ntn;
;   const int k0 = kt * 64, n0 = nt * 64;
;   int tidc = TIDX(p); OPAQUE(tidc);
;   __syncthreads();
; #pragma unroll
;   for (int i = 0; i < 2; i++) {
;     const int idx = tidc + i * NTHR;
;     const int kk = idx >> 4, n4 = (idx & 15) * 4, n = n0 + n4;
;     float4 v = make_float4(0.f, 0.f, 0.f, 0.f);
;     if (n < N) v = *(const float4*)(src + (size_t)(k0 + kk) * N + n);
;     t[kk * 65 + n4] = v.x; t[kk * 65 + n4 + 1] = v.y; t[kk * 65 + n4 + 2] = v.z; t[kk * 65 + n4 + 3] = v.w;
;   }
.LBB0_826:
	s_add_i32 s3, s1, 0xffffdec0
	s_lshr_b32 s6, s3, 5
	s_waitcnt vmcnt(0)
	v_mov_b32_e32 v14, v188
	s_lshl_b32 s2, s6, 6
	s_lshl_b32 s6, s6, 11
	s_lshl_b32 s3, s3, 6
	s_sub_i32 s3, s3, s6
	v_lshlrev_b32_e32 v0, 2, v14
	v_and_b32_e32 v0, 60, v0
	v_or_b32_e32 v2, s3, v0
	v_readlane_b32 s8, v253, 3
	s_movk_i32 s6, 0x800
	v_ashrrev_i32_e32 v3, 31, v2
	v_readlane_b32 s9, v253, 4
	v_cmp_gt_i32_e32 vcc, s6, v2
	s_waitcnt lgkmcnt(0)
	v_mov_b32_e32 v4, 0
	v_lshl_add_u64 v[8:9], v[2:3], 2, s[8:9]
	v_ashrrev_i32_e32 v3, 4, v14
	v_mov_b32_e32 v2, 0
	v_mov_b32_e32 v5, 0
	v_mov_b32_e32 v6, 0
	v_mov_b32_e32 v7, 0
	s_barrier
	v_readlane_b32 s10, v253, 5
	v_readlane_b32 s11, v253, 6
	v_readlane_b32 s12, v253, 7
	v_readlane_b32 s13, v253, 8
	v_readlane_b32 s14, v253, 9
	v_readlane_b32 s15, v253, 10
	v_readlane_b32 s16, v253, 11
	v_readlane_b32 s17, v253, 12
	v_readlane_b32 s18, v253, 13
	v_readlane_b32 s19, v253, 14
	v_readlane_b32 s20, v253, 15
	v_readlane_b32 s21, v253, 16
	v_readlane_b32 s22, v253, 17
	v_readlane_b32 s23, v253, 18
	s_and_saveexec_b64 s[6:7], vcc
	s_cbranch_execz .LBB0_828
	v_add_u32_e32 v4, s2, v3
	v_ashrrev_i32_e32 v5, 31, v4
	v_lshlrev_b64 v[4:5], 13, v[4:5]
	v_lshl_add_u64 v[4:5], v[8:9], 0, v[4:5]
	v_mov_b32_e32 v200, 0x40000
	v_mov_b32_e32 v201, 0
	v_lshl_add_u64 v[202:203], v[4:5], 0, v[200:201]
	global_load_dwordx4 v[4:7], v[4:5], off
	global_load_dwordx4 v[204:207], v[202:203], off

; #define OPAQUE(x) asm volatile("" : "+v"(x))
; #define TIDX(p) ((p).wv * 64 + (int)__builtin_amdgcn_mbcnt_hi(~0u, __builtin_amdgcn_mbcnt_lo(~0u, 0u)))
; DI void cvt_tile(const PX& p, const float* __restrict__ src, bfu* __restrict__ dst, int K, int N, int tile, float* t, bool perm_in = false) {
;   const int ntn = (N + 63) >> 6;
;   const int kt = tile / ntn, nt = tile - kt * ntn;
;   const int k0 = kt * 64, n0 = nt * 64;
;   int tidc = TIDX(p); OPAQUE(tidc);
;   __syncthreads();
; #pragma unroll
;   for (int i = 0; i < 2; i++) {
;     const int idx = tidc + i * NTHR;
;     const int kk = idx >> 4, n4 = (idx & 15) * 4, n = n0 + n4;
;     float4 v = make_float4(0.f, 0.f, 0.f, 0.f);
;     if (n < N) v = *(const float4*)(src + (size_t)(k0 + kk) * N + n);
;     t[kk * 65 + n4] = v.x; t[kk * 65 + n4 + 1] = v.y; t[kk * 65 + n4 + 2] = v.z; t[kk * 65 + n4 + 3] = v.w;
;   }
.LBB0_834:
	s_add_i32 s3, s1, 0xffffe040
	s_lshr_b32 s6, s3, 5
	s_waitcnt vmcnt(0)
	v_mov_b32_e32 v14, v188
	s_lshl_b32 s2, s6, 6
	s_lshl_b32 s6, s6, 11
	s_lshl_b32 s3, s3, 6
	s_sub_i32 s3, s3, s6
	v_lshlrev_b32_e32 v0, 2, v14
	v_and_b32_e32 v0, 60, v0
	v_or_b32_e32 v2, s3, v0
	v_readlane_b32 s8, v252, 51
	s_movk_i32 s6, 0x800
	v_ashrrev_i32_e32 v3, 31, v2
	v_readlane_b32 s22, v253, 1
	v_readlane_b32 s23, v253, 2
	v_cmp_gt_i32_e32 vcc, s6, v2
	s_waitcnt lgkmcnt(0)
	v_mov_b32_e32 v4, 0
	v_lshl_add_u64 v[8:9], v[2:3], 2, s[22:23]
	v_ashrrev_i32_e32 v3, 4, v14
	v_mov_b32_e32 v2, 0
	v_mov_b32_e32 v5, 0
	v_mov_b32_e32 v6, 0
	v_mov_b32_e32 v7, 0
	s_barrier
	v_readlane_b32 s9, v252, 52
	v_readlane_b32 s10, v252, 53
	v_readlane_b32 s11, v252, 54
	v_readlane_b32 s12, v252, 55
	v_readlane_b32 s13, v252, 56
	v_readlane_b32 s14, v252, 57
	v_readlane_b32 s15, v252, 58
	v_readlane_b32 s16, v252, 59
	v_readlane_b32 s17, v252, 60
	v_readlane_b32 s18, v252, 61
	v_readlane_b32 s19, v252, 62
	v_readlane_b32 s20, v252, 63
	v_readlane_b32 s21, v253, 0
	s_and_saveexec_b64 s[6:7], vcc
	s_cbranch_execz .LBB0_836
	v_add_u32_e32 v4, s2, v3
	v_ashrrev_i32_e32 v5, 31, v4
	v_lshlrev_b64 v[4:5], 13, v[4:5]
	v_lshl_add_u64 v[4:5], v[8:9], 0, v[4:5]
	v_mov_b32_e32 v200, 0x40000
	v_mov_b32_e32 v201, 0
	v_lshl_add_u64 v[202:203], v[4:5], 0, v[200:201]
	global_load_dwordx4 v[4:7], v[4:5], off
	global_load_dwordx4 v[204:207], v[202:203], off

; #define OPAQUE(x) asm volatile("" : "+v"(x))
; #define TIDX(p) ((p).wv * 64 + (int)__builtin_amdgcn_mbcnt_hi(~0u, __builtin_amdgcn_mbcnt_lo(~0u, 0u)))
; DI unsigned pack2(float a, float b) { f32x2_t v = {a, b}; bf16x2_t r = __builtin_convertvector(v, bf16x2_t); return __builtin_bit_cast(unsigned, r); }
; DI void cvt_tile(const PX& p, const float* __restrict__ src, bfu* __restrict__ dst, int K, int N, int tile, float* t, bool perm_in = false) {
;   const int ntn = (N + 63) >> 6;
;   const int kt = tile / ntn, nt = tile - kt * ntn;
;   const int k0 = kt * 64, n0 = nt * 64;
;   int tidc = TIDX(p); OPAQUE(tidc);
;   __syncthreads();
; #pragma unroll
;   for (int i = 0; i < 2; i++) {
;     const int idx = tidc + i * NTHR;
;     const int kk = idx >> 4, n4 = (idx & 15) * 4, n = n0 + n4;
;     float4 v = make_float4(0.f, 0.f, 0.f, 0.f);
;     if (n < N) v = *(const float4*)(src + (size_t)(k0 + kk) * N + n);
;     t[kk * 65 + n4] = v.x; t[kk * 65 + n4 + 1] = v.y; t[kk * 65 + n4 + 2] = v.z; t[kk * 65 + n4 + 3] = v.w;
;   }
;   __syncthreads();
;   {
;     const int nn = tidc >> 3, k8 = (tidc & 7) * 8, n = n0 + nn;
;     if (n < N) {
;       uint4 o;
;       o.x = pack2(t[(k8 + 0) * 65 + nn], t[(k8 + 1) * 65 + nn]);
;       o.y = pack2(t[(k8 + 2) * 65 + nn], t[(k8 + 3) * 65 + nn]);
;       o.z = pack2(t[(k8 + 4) * 65 + nn], t[(k8 + 5) * 65 + nn]);
;       o.w = pack2(t[(k8 + 6) * 65 + nn], t[(k8 + 7) * 65 + nn]);
;       const int dn = (!perm_in || n < 5376 || n >= 6160) ? n : (n < 5392 ? n + 768 : n - 16);
;       *(uint4*)(dst + (size_t)dn * K + k0 + k8) = o;
;     }
;   }
; }
; DI void convert_mixer(const PX& p, int l, int tile, float* sm) {
;     ...
;   else if (tile < 7200) cvt_tile(p, p.in[34] + (size_t)l * 2048 * 2048, W1 + W1_WOUT, 2048, 2048, tile - 6176, sm);
.LBB0_842:
	s_add_i32 s3, s1, 0xffffe440
	s_lshr_b32 s6, s3, 5
	s_waitcnt vmcnt(0)
	v_mov_b32_e32 v15, v188
	s_lshl_b32 s2, s6, 6
	s_lshl_b32 s6, s6, 11
	s_lshl_b32 s3, s3, 6
	s_sub_i32 s3, s3, s6
	v_lshlrev_b32_e32 v0, 2, v15
	v_and_b32_e32 v0, 60, v0
	v_or_b32_e32 v2, s3, v0
	v_readlane_b32 s8, v253, 3
	s_movk_i32 s6, 0x800
	v_ashrrev_i32_e32 v3, 31, v2
	v_readlane_b32 s12, v253, 7
	v_readlane_b32 s13, v253, 8
	v_cmp_gt_i32_e32 vcc, s6, v2
	s_waitcnt lgkmcnt(0)
	v_mov_b32_e32 v4, 0
	v_lshl_add_u64 v[8:9], v[2:3], 2, s[12:13]
	v_ashrrev_i32_e32 v3, 4, v15
	v_mov_b32_e32 v2, 0
	v_mov_b32_e32 v5, 0
	v_mov_b32_e32 v6, 0
	v_mov_b32_e32 v7, 0
	s_barrier
	v_readlane_b32 s9, v253, 4
	v_readlane_b32 s10, v253, 5
	v_readlane_b32 s11, v253, 6
	v_readlane_b32 s14, v253, 9
	v_readlane_b32 s15, v253, 10
	v_readlane_b32 s16, v253, 11
	v_readlane_b32 s17, v253, 12
	v_readlane_b32 s18, v253, 13
	v_readlane_b32 s19, v253, 14
	v_readlane_b32 s20, v253, 15
	v_readlane_b32 s21, v253, 16
	v_readlane_b32 s22, v253, 17
	v_readlane_b32 s23, v253, 18
	s_and_saveexec_b64 s[6:7], vcc
	s_cbranch_execz .LBB0_844
	v_add_u32_e32 v4, s2, v3
	v_ashrrev_i32_e32 v5, 31, v4
	v_lshlrev_b64 v[4:5], 13, v[4:5]
	v_lshl_add_u64 v[4:5], v[8:9], 0, v[4:5]
	v_mov_b32_e32 v200, 0x40000
	v_mov_b32_e32 v201, 0
	v_lshl_add_u64 v[202:203], v[4:5], 0, v[200:201]
	global_load_dwordx4 v[4:7], v[4:5], off
	global_load_dwordx4 v[204:207], v[202:203], off
.LBB0_844:
	s_or_b64 exec, exec, s[6:7]
	v_lshlrev_b32_e32 v0, 2, v0
	s_movk_i32 s6, 0x104
	v_mad_u64_u32 v[10:11], s[6:7], v3, s6, v[0:1]
	v_add_u32_e32 v3, 0x200, v15
	s_waitcnt vmcnt(1)
	ds_write2_b32 v10, v4, v5 offset1:1
	ds_write2_b32 v10, v6, v7 offset0:2 offset1:3
	v_ashrrev_i32_e32 v6, 4, v3
	v_mov_b32_e32 v3, 0
	v_mov_b32_e32 v4, 0
	v_mov_b32_e32 v5, 0
	s_and_saveexec_b64 s[6:7], vcc
	s_cbranch_execz .LBB0_846
	v_add_u32_e32 v2, s2, v6
	v_ashrrev_i32_e32 v3, 31, v2
	v_lshlrev_b64 v[2:3], 13, v[2:3]
	v_lshl_add_u64 v[2:3], v[8:9], 0, v[2:3]
	s_waitcnt vmcnt(0)
	v_mov_b32_e32 v2, v204
	v_mov_b32_e32 v3, v205
	v_mov_b32_e32 v4, v206
	v_mov_b32_e32 v5, v207

; #define OPAQUE(x) asm volatile("" : "+v"(x))
; #define TIDX(p) ((p).wv * 64 + (int)__builtin_amdgcn_mbcnt_hi(~0u, __builtin_amdgcn_mbcnt_lo(~0u, 0u)))
; DI unsigned pack2(float a, float b) { f32x2_t v = {a, b}; bf16x2_t r = __builtin_convertvector(v, bf16x2_t); return __builtin_bit_cast(unsigned, r); }
; DI void cvt_tile(const PX& p, const float* __restrict__ src, bfu* __restrict__ dst, int K, int N, int tile, float* t, bool perm_in = false) {
;   const int ntn = (N + 63) >> 6;
;   const int kt = tile / ntn, nt = tile - kt * ntn;
;   const int k0 = kt * 64, n0 = nt * 64;
;   int tidc = TIDX(p); OPAQUE(tidc);
;   __syncthreads();
; #pragma unroll
;   for (int i = 0; i < 2; i++) {
;     const int idx = tidc + i * NTHR;
;     const int kk = idx >> 4, n4 = (idx & 15) * 4, n = n0 + n4;
;     float4 v = make_float4(0.f, 0.f, 0.f, 0.f);
;     if (n < N) v = *(const float4*)(src + (size_t)(k0 + kk) * N + n);
;     t[kk * 65 + n4] = v.x; t[kk * 65 + n4 + 1] = v.y; t[kk * 65 + n4 + 2] = v.z; t[kk * 65 + n4 + 3] = v.w;
;   }
;   __syncthreads();
;   {
;     const int nn = tidc >> 3, k8 = (tidc & 7) * 8, n = n0 + nn;
;     if (n < N) {
;       uint4 o;
;       o.x = pack2(t[(k8 + 0) * 65 + nn], t[(k8 + 1) * 65 + nn]);
;       o.y = pack2(t[(k8 + 2) * 65 + nn], t[(k8 + 3) * 65 + nn]);
;       o.z = pack2(t[(k8 + 4) * 65 + nn], t[(k8 + 5) * 65 + nn]);
;       o.w = pack2(t[(k8 + 6) * 65 + nn], t[(k8 + 7) * 65 + nn]);
;       const int dn = (!perm_in || n < 5376 || n >= 6160) ? n : (n < 5392 ? n + 768 : n - 16);
;       *(uint4*)(dst + (size_t)dn * K + k0 + k8) = o;
;     }
;   }
; }
; DI void convert_mixer(const PX& p, int l, int tile, float* sm) {
;     ...
;   if (tile < 6176) cvt_tile(p, p.in[6] + (size_t)l * 2048 * NIN, W1 + W1_WIN, 2048, NIN, tile, sm, true);
.LBB0_850:
	s_mul_i32 s2, s0, 0x5391
	s_lshr_b32 s2, s2, 16
	s_sub_i32 s3, s0, s2
	s_bfe_u32 s3, s3, 0xf0001
	s_add_i32 s3, s3, s2
	s_bfe_u32 s2, s3, 0x90007
	s_mul_i32 s3, s2, 0xffffff3f
	s_waitcnt vmcnt(0)
	v_mov_b32_e32 v14, v188
	s_add_i32 s3, s3, s0
	s_lshl_b32 s0, s2, 6
	v_lshlrev_b32_e32 v0, 2, v14
	s_lshl_b32 s2, s3, 6
	v_and_b32_e32 v0, 60, v0
	v_or_b32_e32 v2, s2, v0
	v_readlane_b32 s8, v252, 3
	s_movk_i32 s3, 0x3010
	v_ashrrev_i32_e32 v3, 31, v2
	v_readlane_b32 s20, v252, 15
	v_readlane_b32 s21, v252, 16
	v_cmp_gt_i32_e32 vcc, s3, v2
	s_waitcnt lgkmcnt(0)
	v_mov_b32_e32 v4, 0
	v_lshl_add_u64 v[8:9], v[2:3], 2, s[20:21]
	v_ashrrev_i32_e32 v3, 4, v14
	v_mov_b32_e32 v2, 0
	v_mov_b32_e32 v5, 0
	v_mov_b32_e32 v6, 0
	v_mov_b32_e32 v7, 0
	s_barrier
	v_readlane_b32 s9, v252, 4
	v_readlane_b32 s10, v252, 5
	v_readlane_b32 s11, v252, 6
	v_readlane_b32 s12, v252, 7
	v_readlane_b32 s13, v252, 8
	v_readlane_b32 s14, v252, 9
	v_readlane_b32 s15, v252, 10
	v_readlane_b32 s16, v252, 11
	v_readlane_b32 s17, v252, 12
	v_readlane_b32 s18, v252, 13
	v_readlane_b32 s19, v252, 14
	v_readlane_b32 s22, v252, 17
	v_readlane_b32 s23, v252, 18
	s_and_saveexec_b64 s[6:7], vcc
	s_cbranch_execz .LBB0_852
	v_add_u32_e32 v4, s0, v3
	s_mov_b32 s3, 0xc040
	v_mad_i64_i32 v[4:5], s[8:9], v4, s3, v[8:9]
	v_mov_b32_e32 v200, 0x180800
	v_mov_b32_e32 v201, 0
	v_lshl_add_u64 v[202:203], v[4:5], 0, v[200:201]
	global_load_dwordx4 v[4:7], v[4:5], off
	global_load_dwordx4 v[204:207], v[202:203], off
.LBB0_852:
	s_or_b64 exec, exec, s[6:7]
	v_lshlrev_b32_e32 v0, 2, v0
	s_movk_i32 s3, 0x104
	v_mad_u64_u32 v[10:11], s[6:7], v3, s3, v[0:1]
	v_add_u32_e32 v3, 0x200, v14
	s_waitcnt vmcnt(1)
	ds_write2_b32 v10, v4, v5 offset1:1
	ds_write2_b32 v10, v6, v7 offset0:2 offset1:3
	v_ashrrev_i32_e32 v6, 4, v3
	v_mov_b32_e32 v3, 0
	v_mov_b32_e32 v4, 0
	v_mov_b32_e32 v5, 0
	s_and_saveexec_b64 s[6:7], vcc
	s_cbranch_execz .LBB0_854
	v_add_u32_e32 v2, s0, v6
	s_mov_b32 s3, 0xc040
	v_mad_i64_i32 v[2:3], s[8:9], v2, s3, v[8:9]
	s_waitcnt vmcnt(0)
	v_mov_b32_e32 v2, v204
	v_mov_b32_e32 v3, v205
	v_mov_b32_e32 v4, v206
	v_mov_b32_e32 v5, v207
